# up-phase tile remap: 4 overflow tiles moved to CUs with 12 tiles (max 13 instead of 14)
# speedup vs baseline: 1.0081x; 1.0081x over previous
; DI int tid() { int t; asm volatile("v_mov_b32 %0, %1" : "=v"(t) : "v"((int)threadIdx.x)); return t; }
; DI int bid() { int b; asm volatile("s_mov_b32 %0, %1" : "=s"(b) : "s"((int)blockIdx.x)); return b; }
; template <int MB, class Epi>
; DI void gemm_tile(const u16* __restrict__ A, int lda, int row0, int Mrows, const u16* __restrict__ Bt, int ldb, int K, char* smem, Epi& epi, int rot) {
;   char* As = smem;
;   char* Bs = smem + 65536;
;   const unsigned lds_base = (unsigned)(size_t)(lds_char*)smem;
;   const int t = tid(), lane = t & 63, w = __builtin_amdgcn_readfirstlane(t >> 6), wm = w >> 2, wn = w & 3, r = lane & 31, h = lane >> 5;
;   constexpr int NAJ = MB;
;   const int lr = t >> 3;
;   const int lch = (t & 7) ^ ((lr >> 1) & 7);
;   unsigned aoff[NAJ];
; #pragma unroll
;   for (int j = 0; j < NAJ; ++j) {
;     int gr = row0 + lr + 64 * j;
;     gr = gr < 0 ? 0 : (gr > Mrows - 1 ? Mrows - 1 : gr);
;     aoff[j] = (unsigned)gr * (unsigned)lda + lch * 8;
;   }
;   const u16* bp = Bt + (size_t)lr * ldb + lch * 8;
;   f32x16 acc[2][MB];
; #pragma unroll
;   for (int nb = 0; nb < 2; ++nb)
; #pragma unroll
;     for (int mb = 0; mb < MB; ++mb)
; #pragma unroll
;       for (int i = 0; i < 16; ++i) acc[nb][mb][i] = 0.f;
;   const int KT = K >> 6;
;   int kcur = rot % KT;
;     ...
;   GEMM_STAGE(0)
;   asm volatile("s_waitcnt vmcnt(0)" ::: "memory");
;   __syncthreads();
; DI void phase_up(const Params& p, int l, char* smem) {
;   const int rows = (l == 3) ? NLAT : NROWS;
;   const int MT = (rows + 253) / 254;
;   const int MTP = (MT + 7) & ~7;
;   const u16* W = (const u16*)(p.ws + OFF_WUP) + (size_t)l * 5632 * 1024;
;   const u16* H = (const u16*)(p.ws + OFF_H);
;   for (int tile = bid(); tile < MTP * 22; tile += gridDim.x) {
;     int mt, nt;
;     if (!tile_map(tile, 22, MT, mt, nt)) continue;
;     EpiUp e;
;     e.act = (u16*)(p.ws + OFF_ACT); e.cw = p.conv_w + (size_t)l * 3 * 5632; e.cb = p.conv_b + (size_t)l * 5632;
;     e.row0 = mt * 254 - 1; e.Mrows = rows; e.nt = nt; e.edge = (float*)(smem + 131072); e.ostage = (u16*)smem;
;     gemm_tile<4>(H, 1024, mt * 254 - 1, rows, W + (size_t)nt * 256 * 1024, 1024, 1024, smem, e, tile);
.LBB0_772:
	s_mov_b32 s100, s9
	s_cmp_lg_u32 s8, 0x92
	s_cbranch_scc1 .Lup_nomap
	s_cmp_ge_u32 s9, 0xd00
	s_cbranch_scc1 .LBB0_771
	s_cmp_lt_u32 s9, 0xcfc
	s_cbranch_scc1 .Lup_nomap
	s_cmp_ge_u32 s9, 0xcfe
	s_cselect_b32 s101, 10, 4
	s_add_i32 s100, s9, s101
.Lup_nomap:
	s_ashr_i32 s0, s100, 3
	s_mul_hi_i32 s2, s0, 0x2e8ba2e9
	s_lshr_b32 s14, s2, 31
	s_ashr_i32 s2, s2, 2
	s_add_i32 s2, s2, s14
	s_and_b32 s3, s100, 7
	s_lshl_b32 s14, s2, 3
	s_or_b32 s3, s14, s3
	s_cmp_ge_i32 s3, s8
	s_cbranch_scc1 .LBB0_771
	s_mul_i32 s14, s3, 0xfe
	s_add_i32 s14, s14, -1
	v_mov_b32 v165, v163
	s_movk_i32 s15, 0xffbf
	v_ashrrev_i32_e32 v2, 3, v165
	v_add_u32_e32 v3, s14, v2
	v_min_u32_e32 v4, s13, v3
	v_add_u32_e32 v6, 64, v3
	v_lshrrev_b32_e32 v0, 4, v165
	v_lshlrev_b32_e32 v4, 10, v4
	v_cmp_lt_i32_e32 vcc, -1, v3
	v_min_u32_e32 v6, s13, v6
	v_add_u32_e32 v7, 0x80, v3
	v_xor_b32_e32 v0, v0, v165
	v_cndmask_b32_e32 v4, 0, v4, vcc
	v_lshlrev_b32_e32 v6, 10, v6
	v_cmp_lt_i32_e32 vcc, s15, v3
	v_min_u32_e32 v7, s13, v7
	s_movk_i32 s15, 0xff7f
	v_lshlrev_b32_e32 v0, 3, v0
	v_cndmask_b32_e32 v6, 0, v6, vcc
	v_lshlrev_b32_e32 v7, 10, v7
	v_cmp_lt_i32_e32 vcc, s15, v3
	v_and_b32_e32 v0, 56, v0
	s_mul_i32 s2, s2, 22
	v_cndmask_b32_e32 v7, 0, v7, vcc
	v_or_b32_e32 v8, v7, v0
	v_add_u32_e32 v7, 0xc0, v3
	s_sub_i32 s48, s0, s2
	v_min_u32_e32 v7, s13, v7
	s_movk_i32 s15, 0xff3f
	s_ashr_i32 s49, s48, 31
	v_lshlrev_b32_e32 v7, 10, v7
	v_cmp_lt_i32_e32 vcc, s15, v3
	s_lshl_b64 s[2:3], s[48:49], 19
	s_add_u32 s2, s11, s2
	v_cndmask_b32_e32 v3, 0, v7, vcc
	v_or_b32_e32 v7, v3, v0
	v_ashrrev_i32_e32 v3, 31, v2
	s_addc_u32 s3, s12, s3
	v_lshlrev_b64 v[2:3], 11, v[2:3]
	v_lshl_add_u64 v[2:3], s[2:3], 0, v[2:3]
	s_ashr_i32 s2, s9, 31
	s_lshr_b32 s2, s2, 28
	s_add_i32 s2, s9, s2
	s_and_b32 s2, s2, -16
	v_readfirstlane_b32 s0, v165
	s_sub_i32 s19, s9, s2
	s_lshl_b32 s28, s19, 6
	s_lshl_b32 s2, s0, 4
	v_or_b32_e32 v4, v4, v0
	v_or_b32_e32 v6, v6, v0
	v_lshlrev_b32_e32 v0, 1, v0
	s_ashr_i32 s29, s28, 31
	s_and_b32 s3, s2, 0xfffffc00
	s_bfe_u32 s16, s0, 0x20006
	s_ashr_i32 s15, s0, 8
	v_lshl_add_u64 v[154:155], v[2:3], 0, v[0:1]
	s_lshl_b64 s[36:37], s[28:29], 1
	s_add_i32 s22, s3, 0x10000
	v_lshl_add_u64 v[2:3], v[154:155], 0, s[36:37]
	s_add_u32 s36, s84, s36
	s_addc_u32 s37, s85, s37
	v_lshlrev_b32_e32 v0, 1, v4
	v_lshl_add_u64 v[10:11], s[36:37], 0, v[0:1]
	s_mov_b32 m0, s3
	s_nop 0
	global_load_lds_dwordx4 v[10:11], off
	v_lshlrev_b32_e32 v10, 1, v6
	v_mov_b32_e32 v11, v1
	v_lshl_add_u64 v[12:13], s[36:37], 0, v[10:11]
	s_add_i32 s2, s3, 0x2000
	s_mov_b32 m0, s2
	s_nop 0
	global_load_lds_dwordx4 v[12:13], off
	v_lshlrev_b32_e32 v12, 1, v8
	v_mov_b32_e32 v13, v1
	v_lshl_add_u64 v[14:15], s[36:37], 0, v[12:13]
	s_add_i32 s2, s3, 0x4000
	s_mov_b32 m0, s2
	s_nop 0
	global_load_lds_dwordx4 v[14:15], off
	v_lshlrev_b32_e32 v14, 1, v7
	v_mov_b32_e32 v15, v1
	v_lshl_add_u64 v[16:17], s[36:37], 0, v[14:15]
	s_add_i32 s23, s3, 0x6000
	s_mov_b32 m0, s23
	s_nop 0
	global_load_lds_dwordx4 v[16:17], off
	s_mov_b32 m0, s22
	s_nop 0
	global_load_lds_dwordx4 v[2:3], off
	s_add_i32 s2, s3, 0x12000
	v_lshl_add_u64 v[16:17], v[2:3], 0, s[4:5]
	s_mov_b32 m0, s2
	s_nop 0
	global_load_lds_dwordx4 v[16:17], off
	s_add_i32 s2, s3, 0x14000
	v_lshl_add_u64 v[16:17], v[2:3], 0, s[6:7]
	s_mov_b32 m0, s2
	s_nop 0
	global_load_lds_dwordx4 v[16:17], off
	s_add_i32 s2, s3, 0x16000
	v_lshl_add_u64 v[2:3], v[2:3], 0, s[34:35]
	s_mov_b32 m0, s2
	s_nop 0
	global_load_lds_dwordx4 v[2:3], off
	s_lshl_b32 s2, s16, 13
	s_lshl_b32 s17, s15, 14
	s_bitset1_b32 s2, 16
	s_add_i32 s25, s28, 64
	v_lshrrev_b32_e32 v5, 5, v165
	v_and_b32_e32 v167, 31, v165
	v_bfe_u32 v2, v165, 1, 3
	s_cmp_lt_i32 s19, 15
	v_lshlrev_b32_e32 v3, 7, v167
	v_bitop3_b32 v5, v5, v2, 1 bitop3:0x6c
	s_cselect_b32 s28, s25, 0
	v_lshl_or_b32 v5, v5, 4, v3
	s_ashr_i32 s29, s28, 31
	v_bfe_u32 v169, v165, 5, 1
	v_or_b32_e32 v164, s17, v5
	s_lshl_b64 s[28:29], s[28:29], 1
	s_waitcnt vmcnt(0)
	s_barrier
; template <int MB, class Epi>
; DI void gemm_tile(const u16* __restrict__ A, int lda, int row0, int Mrows, const u16* __restrict__ Bt, int ldb, int K, char* smem, Epi& epi, int rot) {
;     ...
;   f32x16 acc[2][MB];
; #pragma unroll
;   for (int nb = 0; nb < 2; ++nb)
; #pragma unroll
;     for (int mb = 0; mb < MB; ++mb)
; #pragma unroll
;       for (int i = 0; i < 16; ++i) acc[nb][mb][i] = 0.f;
;     ...
;   const int sw = (r >> 1) & 7;
;   int foff[4];
; #pragma unroll
;   for (int ks = 0; ks < 4; ++ks) foff[ks] = r * 128 + (((2 * ks + h) ^ sw) << 4);
;   bf8 af[2][MB], bfr[2][2];
;   {
;     const char* as0 = As + wm * (32 * MB) * 128;
;     const char* bs0 = Bs + wn * 64 * 128;
; #pragma unroll
;     for (int mb = 0; mb < MB; ++mb) af[0][mb] = *(const bf8*)(as0 + mb * 32 * 128 + foff[0]);
; #pragma unroll
;     for (int nb = 0; nb < 2; ++nb) bfr[0][nb] = *(const bf8*)(bs0 + nb * 32 * 128 + foff[0]);
;   }
;   const int kbase = rot % KT;
;   if (KT > 1) {
;     const int k1_ = (kbase + 1 >= KT) ? kbase + 1 - KT : kbase + 1;
;     const int ko_ = k1_ * 64;
; #pragma unroll
;     for (int pc = 0; pc < 3; ++pc) GEMM_PIECE(1, pc)
;   }
	v_bitop3_b32 v7, v169, v2, 2 bitop3:0x36
	ds_read_b128 v[146:149], v164
	ds_read_b128 v[142:145], v164 offset:4096
	ds_read_b128 v[134:137], v164 offset:8192
	s_waitcnt vmcnt(0)
	ds_read_b128 v[130:133], v164 offset:12288
	s_add_u32 s28, s84, s28
	v_lshl_or_b32 v171, v7, 4, v3
	v_bitop3_b32 v7, v169, v2, 4 bitop3:0x36
	v_bitop3_b32 v2, v169, v2, 6 bitop3:0x36
	v_or_b32_e32 v166, s2, v5
	s_addc_u32 s29, s85, s29
	v_lshl_or_b32 v170, v7, 4, v3
	v_lshl_or_b32 v168, v2, 4, v3
	ds_read_b128 v[150:153], v166
	ds_read_b128 v[138:141], v166 offset:4096
	s_add_i32 s25, s3, 0x8000
	v_lshl_add_u64 v[2:3], s[28:29], 0, v[0:1]
	s_mov_b32 m0, s25
	s_nop 0
	global_load_lds_dwordx4 v[2:3], off
	v_lshl_add_u64 v[2:3], s[28:29], 0, v[10:11]
	s_add_i32 s25, s3, 0xa000
	s_mov_b32 m0, s25
	s_nop 0
	global_load_lds_dwordx4 v[2:3], off
	v_lshl_add_u64 v[2:3], s[28:29], 0, v[12:13]
	s_add_i32 s25, s3, 0xc000
	s_mov_b32 m0, s25
	s_nop 0
	global_load_lds_dwordx4 v[2:3], off
	v_mov_b32_e32 v2, 0
	s_mov_b32 s18, 0
	v_lshl_add_u64 v[156:157], s[84:85], 0, v[14:15]
	v_lshlrev_b32_e32 v0, 1, v4
	v_lshlrev_b32_e32 v158, 1, v6
	v_lshlrev_b32_e32 v160, 1, v8
	s_mov_b32 s25, s19
	v_mov_b32_e32 v3, v2
	v_mov_b32_e32 v4, v2
	v_mov_b32_e32 v5, v2
	v_mov_b32_e32 v6, v2
	v_mov_b32_e32 v7, v2
	v_mov_b32_e32 v8, v2
	v_mov_b32_e32 v9, v2
	v_mov_b32_e32 v10, v2
	v_mov_b32_e32 v11, v2
	v_mov_b32_e32 v12, v2
	v_mov_b32_e32 v13, v2
	v_mov_b32_e32 v14, v2
	v_mov_b32_e32 v15, v2
	v_mov_b32_e32 v16, v2
	v_mov_b32_e32 v17, v2
	v_mov_b32_e32 v18, v2
	v_mov_b32_e32 v19, v2
	v_mov_b32_e32 v20, v2
	v_mov_b32_e32 v21, v2
	v_mov_b32_e32 v22, v2
	v_mov_b32_e32 v23, v2
	v_mov_b32_e32 v24, v2
	v_mov_b32_e32 v25, v2
	v_mov_b32_e32 v26, v2
	v_mov_b32_e32 v27, v2
	v_mov_b32_e32 v28, v2
	v_mov_b32_e32 v29, v2
	v_mov_b32_e32 v30, v2
	v_mov_b32_e32 v31, v2
	v_mov_b32_e32 v32, v2
	v_mov_b32_e32 v33, v2
	v_mov_b32_e32 v50, v2
	v_mov_b32_e32 v51, v2
	v_mov_b32_e32 v52, v2
	v_mov_b32_e32 v53, v2
	v_mov_b32_e32 v54, v2
	v_mov_b32_e32 v55, v2
	v_mov_b32_e32 v56, v2
	v_mov_b32_e32 v57, v2
	v_mov_b32_e32 v58, v2
	v_mov_b32_e32 v59, v2
	v_mov_b32_e32 v60, v2
	v_mov_b32_e32 v61, v2
	v_mov_b32_e32 v62, v2
	v_mov_b32_e32 v63, v2
	v_mov_b32_e32 v64, v2
	v_mov_b32_e32 v65, v2
	v_mov_b32_e32 v98, v2
	v_mov_b32_e32 v99, v2
	v_mov_b32_e32 v100, v2
	v_mov_b32_e32 v101, v2
	v_mov_b32_e32 v102, v2
	v_mov_b32_e32 v103, v2
	v_mov_b32_e32 v104, v2
	v_mov_b32_e32 v105, v2
	v_mov_b32_e32 v106, v2
	v_mov_b32_e32 v107, v2
	v_mov_b32_e32 v108, v2
	v_mov_b32_e32 v109, v2
	v_mov_b32_e32 v110, v2
	v_mov_b32_e32 v111, v2
	v_mov_b32_e32 v112, v2
	v_mov_b32_e32 v113, v2
	v_mov_b32_e32 v114, v2
	v_mov_b32_e32 v115, v2
	v_mov_b32_e32 v116, v2
	v_mov_b32_e32 v117, v2
	v_mov_b32_e32 v118, v2
	v_mov_b32_e32 v119, v2
	v_mov_b32_e32 v120, v2
	v_mov_b32_e32 v121, v2
	v_mov_b32_e32 v122, v2
	v_mov_b32_e32 v123, v2
	v_mov_b32_e32 v124, v2
	v_mov_b32_e32 v125, v2
	v_mov_b32_e32 v126, v2
	v_mov_b32_e32 v127, v2
	v_mov_b32_e32 v128, v2
	v_mov_b32_e32 v129, v2
	v_mov_b32_e32 v82, v2
	v_mov_b32_e32 v83, v2
	v_mov_b32_e32 v84, v2
	v_mov_b32_e32 v85, v2
	v_mov_b32_e32 v86, v2
	v_mov_b32_e32 v87, v2
	v_mov_b32_e32 v88, v2
	v_mov_b32_e32 v89, v2
	v_mov_b32_e32 v90, v2
	v_mov_b32_e32 v91, v2
	v_mov_b32_e32 v92, v2
	v_mov_b32_e32 v93, v2
	v_mov_b32_e32 v94, v2
	v_mov_b32_e32 v95, v2
	v_mov_b32_e32 v96, v2
	v_mov_b32_e32 v97, v2
	v_mov_b32_e32 v66, v2
	v_mov_b32_e32 v67, v2
	v_mov_b32_e32 v68, v2
	v_mov_b32_e32 v69, v2
	v_mov_b32_e32 v70, v2
	v_mov_b32_e32 v71, v2
	v_mov_b32_e32 v72, v2
	v_mov_b32_e32 v73, v2
	v_mov_b32_e32 v74, v2
	v_mov_b32_e32 v75, v2
	v_mov_b32_e32 v76, v2
	v_mov_b32_e32 v77, v2
	v_mov_b32_e32 v78, v2
	v_mov_b32_e32 v79, v2
	v_mov_b32_e32 v80, v2
	v_mov_b32_e32 v81, v2
	v_mov_b32_e32 v34, v2
	v_mov_b32_e32 v35, v2
	v_mov_b32_e32 v36, v2
	v_mov_b32_e32 v37, v2
	v_mov_b32_e32 v38, v2
	v_mov_b32_e32 v39, v2
	v_mov_b32_e32 v40, v2
	v_mov_b32_e32 v41, v2
	v_mov_b32_e32 v42, v2
	v_mov_b32_e32 v43, v2
	v_mov_b32_e32 v44, v2
	v_mov_b32_e32 v45, v2
	v_mov_b32_e32 v46, v2
	v_mov_b32_e32 v47, v2
	v_mov_b32_e32 v48, v2
	v_mov_b32_e32 v49, v2

; #define LAS __attribute__((address_space(3)))
; __global__ void __launch_bounds__(512, 2) fwd_megakernel(Params p, int ph_lo, int ph_hi) {
;   __shared__ __attribute__((aligned(16))) char smem[SMEM_BYTES];
;   __shared__ __attribute__((aligned(16))) unsigned xb_words[4];
;   cg::grid_group grid = cg::this_grid();
;   if (threadIdx.x < 4) xb_words[threadIdx.x] = 0u;
;   __syncthreads();
;   const XcdBarrier xb = xcd_barrier_post((unsigned*)(p.ws + OFF_BAR), (volatile LAS unsigned*)xb_words);
	.amdhsa_kernel _Z14fwd_megakernel6Paramsii
		.amdhsa_group_segment_fixed_size 135184
		.amdhsa_private_segment_fixed_size 0
		.amdhsa_kernarg_size 440
		.amdhsa_user_sgpr_count 2
		.amdhsa_user_sgpr_dispatch_ptr 0
		.amdhsa_user_sgpr_queue_ptr 0
		.amdhsa_user_sgpr_kernarg_segment_ptr 1
		.amdhsa_user_sgpr_dispatch_id 0
		.amdhsa_user_sgpr_kernarg_preload_length 0
		.amdhsa_user_sgpr_kernarg_preload_offset 0
		.amdhsa_user_sgpr_private_segment_size 0
		.amdhsa_uses_dynamic_stack 0
		.amdhsa_enable_private_segment 0
		.amdhsa_system_sgpr_workgroup_id_x 1
		.amdhsa_system_sgpr_workgroup_id_y 0
		.amdhsa_system_sgpr_workgroup_id_z 0
		.amdhsa_system_sgpr_workgroup_info 0
		.amdhsa_system_vgpr_workitem_id 2
		.amdhsa_next_free_vgpr 237
		.amdhsa_next_free_sgpr 102
		.amdhsa_accum_offset 240
		.amdhsa_reserve_vcc 1
		.amdhsa_float_round_mode_32 0
		.amdhsa_float_round_mode_16_64 0
		.amdhsa_float_denorm_mode_32 3
		.amdhsa_float_denorm_mode_16_64 3
		.amdhsa_dx10_clamp 1
		.amdhsa_ieee_mode 1
		.amdhsa_fp16_overflow 0
		.amdhsa_tg_split 0
		.amdhsa_exception_fp_ieee_invalid_op 0
		.amdhsa_exception_fp_denorm_src 0
		.amdhsa_exception_fp_ieee_div_zero 0
		.amdhsa_exception_fp_ieee_overflow 0
		.amdhsa_exception_fp_ieee_underflow 0
		.amdhsa_exception_fp_ieee_inexact 0
		.amdhsa_exception_int_div_zero 0
	.end_amdhsa_kernel

; #define LAS __attribute__((address_space(3)))
; __global__ void __launch_bounds__(512, 2) fwd_megakernel(Params p, int ph_lo, int ph_hi) {
;   __shared__ __attribute__((aligned(16))) char smem[SMEM_BYTES];
;   __shared__ __attribute__((aligned(16))) unsigned xb_words[4];
;   cg::grid_group grid = cg::this_grid();
;   if (threadIdx.x < 4) xb_words[threadIdx.x] = 0u;
;   __syncthreads();
;   const XcdBarrier xb = xcd_barrier_post((unsigned*)(p.ws + OFF_BAR), (volatile LAS unsigned*)xb_words);
amdhsa.kernels:
  - .agpr_count:     0
    .args:
      - .offset:         0
        .size:           176
        .value_kind:     by_value
      - .offset:         176
        .size:           4
        .value_kind:     by_value
      - .offset:         180
        .size:           4
        .value_kind:     by_value
      - .offset:         184
        .size:           4
        .value_kind:     hidden_block_count_x
      - .offset:         188
        .size:           4
        .value_kind:     hidden_block_count_y
      - .offset:         192
        .size:           4
        .value_kind:     hidden_block_count_z
      - .offset:         196
        .size:           2
        .value_kind:     hidden_group_size_x
      - .offset:         198
        .size:           2
        .value_kind:     hidden_group_size_y
      - .offset:         200
        .size:           2
        .value_kind:     hidden_group_size_z
      - .offset:         202
        .size:           2
        .value_kind:     hidden_remainder_x
      - .offset:         204
        .size:           2
        .value_kind:     hidden_remainder_y
      - .offset:         206
        .size:           2
        .value_kind:     hidden_remainder_z
      - .offset:         224
        .size:           8
        .value_kind:     hidden_global_offset_x
      - .offset:         232
        .size:           8
        .value_kind:     hidden_global_offset_y
      - .offset:         240
        .size:           8
        .value_kind:     hidden_global_offset_z
      - .offset:         248
        .size:           2
        .value_kind:     hidden_grid_dims
      - .offset:         272
        .size:           8
        .value_kind:     hidden_multigrid_sync_arg
    .group_segment_fixed_size: 135184
    .kernarg_segment_align: 8
    .kernarg_segment_size: 440
    .language:       OpenCL C
    .language_version:
      - 2
      - 0
    .max_flat_workgroup_size: 512
    .name:           _Z14fwd_megakernel6Paramsii
    .private_segment_fixed_size: 0
    .sgpr_count:     108
    .sgpr_spill_count: 179
    .symbol:         _Z14fwd_megakernel6Paramsii.kd
    .uniform_work_group_size: 1
    .uses_dynamic_stack: false
    .vgpr_count:     237
    .vgpr_spill_count: 0
    .wavefront_size: 64
